# final RMSNorm phase: the 14 in-ladder gain loads hoisted to the top of each row iteration, removing the per-store vmcnt drains (on top of v9)
# baseline (speedup 1.0000x reference)
; #define GAS __attribute__((address_space(1)))
; __device__ __forceinline__ void final_norm_rows(Frame& F, const bf16* X, float* O, const float* gain) {
;     ...
;     for (int m = gw; m < M; m += NGW) {
;         const GAS v4u* xr = (const GAS v4u*)(X + (size_t)m * D) + F.lane;
;         v4u v[8]; float ss = 0.f;
; #pragma unroll
;         for (int j = 0; j < 8; ++j) { v[j] = xr[64 * j];
;             ss += (bflo(v[j].x) * bflo(v[j].x) + bfhi(v[j].x) * bfhi(v[j].x)) + (bflo(v[j].y) * bflo(v[j].y) + bfhi(v[j].y) * bfhi(v[j].y)) + (bflo(v[j].z) * bflo(v[j].z) + bfhi(v[j].z) * bfhi(v[j].z)) + (bflo(v[j].w) * bflo(v[j].w) + bfhi(v[j].w) * bfhi(v[j].w)); }
;     ...
;         for (int j = 0; j < 8; ++j) { const int col = 8 * (F.lane + 64 * j); const f32x4 g0 = *(const f32x4*)(gain + col), g1 = *(const f32x4*)(gain + col + 4);
.LBB0_1141:
	v_add_co_u32_e32 v38, vcc, s3, v32
	global_load_dwordx4 v[144:147], v[16:17], off offset:2048
	global_load_dwordx4 v[148:151], v[16:17], off offset:2064
	global_load_dwordx4 v[152:155], v[18:19], off
	global_load_dwordx4 v[156:159], v[18:19], off offset:16
	global_load_dwordx4 v[160:163], v[20:21], off
	global_load_dwordx4 v[164:167], v[20:21], off offset:16
	global_load_dwordx4 v[168:171], v[22:23], off
	global_load_dwordx4 v[172:175], v[22:23], off offset:16
	global_load_dwordx4 v[176:179], v[24:25], off
	global_load_dwordx4 v[180:183], v[24:25], off offset:16
	global_load_dwordx4 v[184:187], v[26:27], off
	global_load_dwordx4 v[188:191], v[26:27], off offset:16
	global_load_dwordx4 v[192:195], v[28:29], off
	global_load_dwordx4 v[196:199], v[28:29], off offset:16
	global_load_dwordx4 v[0:3], v[32:33], off
	global_load_dwordx4 v[4:7], v[32:33], off offset:1024
	global_load_dwordx4 v[8:11], v[32:33], off offset:2048
	global_load_dwordx4 v[12:15], v[32:33], off offset:3072
	v_addc_co_u32_e32 v39, vcc, 0, v33, vcc
	global_load_dwordx4 v[78:81], v[16:17], off offset:16
	global_load_dwordx4 v[82:85], v[16:17], off
	global_load_dwordx4 v[34:37], v[38:39], off
	global_load_dwordx4 v[40:43], v[38:39], off offset:1024
	global_load_dwordx4 v[86:89], v[38:39], off offset:2048
	global_load_dwordx4 v[90:93], v[38:39], off offset:3072
	s_add_i32 s2, s2, s4
	v_lshl_add_u64 v[32:33], v[32:33], 0, s[8:9]
	s_cmpk_lt_i32 s2, 0x4000
	s_waitcnt vmcnt(0)
	v_and_b32_e32 v95, 0xffff0000, v1
	v_and_b32_e32 v99, 0xffff0000, v0
	v_and_b32_e32 v98, 0xffff0000, v2
	v_and_b32_e32 v105, 0xffff0000, v5
	v_and_b32_e32 v104, 0xffff0000, v4
	v_and_b32_e32 v67, 0xffff0000, v8
	v_and_b32_e32 v69, 0xffff0000, v9
	v_lshlrev_b32_e32 v94, 16, v1
	v_lshlrev_b32_e32 v97, 16, v0
	v_lshlrev_b32_e32 v96, 16, v2
	v_lshlrev_b32_e32 v100, 16, v3
	v_and_b32_e32 v101, 0xffff0000, v3
	v_lshlrev_b32_e32 v103, 16, v5
	v_lshlrev_b32_e32 v102, 16, v4
	v_and_b32_e32 v109, 0xffff0000, v7
	v_and_b32_e32 v108, 0xffff0000, v6
	v_lshlrev_b32_e32 v66, 16, v8
	v_lshlrev_b32_e32 v68, 16, v9
	v_lshlrev_b32_e32 v52, 16, v13
	v_and_b32_e32 v53, 0xffff0000, v13
	v_and_b32_e32 v55, 0xffff0000, v15
	v_lshlrev_b32_e32 v65, 16, v12
	v_and_b32_e32 v57, 0xffff0000, v12
	v_pk_mov_b32 v[0:1], v[10:11], v[14:15] op_sel:[1,0]
	v_mul_f32_e32 v2, v95, v95
	v_pk_mul_f32 v[12:13], v[98:99], v[98:99]
	v_pk_mul_f32 v[110:111], v[104:105], v[104:105]
	v_mul_f32_e32 v4, v67, v67
	v_mul_f32_e32 v54, v69, v69
	v_lshlrev_b32_e32 v5, 16, v93
	v_and_b32_e32 v3, 0xffff0000, v93
	v_lshlrev_b32_e32 v107, 16, v7
	v_lshlrev_b32_e32 v106, 16, v6
	v_lshlrev_b32_e32 v59, 16, v15
	v_and_b32_e32 v56, 0xffff0000, v10
	v_lshlrev_b32_e32 v61, 16, v14
	v_lshlrev_b32_e32 v60, 16, v11
	v_pk_mul_f32 v[112:113], v[108:109], v[108:109]
	v_mul_f32_e32 v116, v52, v52
	v_mul_f32_e32 v136, v53, v53
	v_and_b32_e32 v63, 0xffff0000, v1
	v_and_b32_e32 v62, 0xffff0000, v0
	v_lshlrev_b32_e32 v45, 16, v35
	v_lshlrev_b32_e32 v44, 16, v34
	v_and_b32_e32 v49, 0xffff0000, v35
	v_and_b32_e32 v48, 0xffff0000, v34
	v_lshlrev_b32_e32 v14, 16, v86
	v_and_b32_e32 v15, 0xffff0000, v86
	v_lshlrev_b32_e32 v34, 16, v87
	v_and_b32_e32 v35, 0xffff0000, v87
	v_lshlrev_b32_e32 v0, 16, v91
	v_and_b32_e32 v1, 0xffff0000, v91
	v_lshlrev_b32_e32 v9, 16, v90
	v_and_b32_e32 v7, 0xffff0000, v90
	v_pk_mov_b32 v[86:87], v[88:89], v[92:93] op_sel:[1,0]
	v_lshlrev_b32_e32 v11, 16, v92
	v_pk_fma_f32 v[90:91], v[94:95], v[94:95], v[2:3] op_sel_hi:[1,1,0]
	v_pk_fma_f32 v[92:93], v[96:97], v[96:97], v[12:13]
	v_pk_fma_f32 v[110:111], v[102:103], v[102:103], v[110:111]
	v_pk_fma_f32 v[118:119], v[66:67], v[66:67], v[4:5] op_sel_hi:[1,1,0]
	v_pk_fma_f32 v[120:121], v[68:69], v[68:69], v[54:55] op_sel_hi:[1,1,0]
	v_lshlrev_b32_e32 v64, 16, v10
	v_pk_mul_f32 v[114:115], v[56:57], v[56:57]
	v_mul_f32_e32 v58, v101, v101
	v_lshlrev_b32_e32 v8, 16, v88
	v_and_b32_e32 v6, 0xffff0000, v88
	v_lshlrev_b32_e32 v10, 16, v89
	v_mov_b32_e32 v88, v97
	v_mov_b32_e32 v89, v99
	v_pk_fma_f32 v[112:113], v[106:107], v[106:107], v[112:113]
	v_mov_b32_e32 v97, v98
	v_pk_add_f32 v[90:91], v[92:93], v[90:91] op_sel:[1,0] op_sel_hi:[0,1]
	v_pk_add_f32 v[98:99], v[110:111], v[110:111] op_sel:[0,1] op_sel_hi:[1,0]
	v_mov_b32_e32 v119, v116
	v_mov_b32_e32 v121, v136
	v_pk_fma_f32 v[114:115], v[64:65], v[64:65], v[114:115]
	v_pk_mul_f32 v[122:123], v[62:63], v[62:63]
	v_pk_fma_f32 v[124:125], v[100:101], v[100:101], v[58:59] op_sel_hi:[1,1,0]
	v_pk_add_f32 v[90:91], v[92:93], v[90:91]
	v_pk_add_f32 v[92:93], v[112:113], v[98:99]
	v_pk_add_f32 v[98:99], v[118:119], v[120:121]
	v_mov_b32_e32 v117, v59
	v_pk_fma_f32 v[110:111], v[60:61], v[60:61], v[122:123]
	v_mov_b32_e32 v58, v124
	v_pk_add_f32 v[98:99], v[114:115], v[98:99]
	v_mov_b32_e32 v116, v90
	v_mul_f32_e32 v140, v55, v55
	v_and_b32_e32 v51, 0xffff0000, v37
	v_and_b32_e32 v50, 0xffff0000, v36
	v_pk_mul_f32 v[126:127], v[48:49], v[48:49]
	v_pk_add_f32 v[90:91], v[124:125], v[90:91]
	v_pk_add_f32 v[92:93], v[112:113], v[92:93] op_sel:[1,0] op_sel_hi:[0,1]
	v_pk_add_f32 v[98:99], v[110:111], v[98:99]
	v_pk_mul_f32 v[110:111], v[58:59], v[116:117]
	v_lshlrev_b32_e32 v47, 16, v37
	v_lshlrev_b32_e32 v46, 16, v36
	v_lshlrev_b32_e32 v37, 16, v41
	v_lshlrev_b32_e32 v36, 16, v40
	v_and_b32_e32 v41, 0xffff0000, v41
	v_and_b32_e32 v40, 0xffff0000, v40
	v_pk_mul_f32 v[128:129], v[50:51], v[50:51]
	v_pk_fma_f32 v[122:123], v[44:45], v[44:45], v[126:127]
	v_mov_b32_e32 v93, v140
	v_mov_b32_e32 v91, v111
	v_lshlrev_b32_e32 v39, 16, v43
	v_lshlrev_b32_e32 v38, 16, v42
	v_and_b32_e32 v43, 0xffff0000, v43
	v_and_b32_e32 v42, 0xffff0000, v42
	v_pk_mul_f32 v[130:131], v[40:41], v[40:41]
; #define GAS __attribute__((address_space(1)))
; __device__ __forceinline__ void final_norm_rows(Frame& F, const bf16* X, float* O, const float* gain) {
;     ...
;         const float rstd = 1.0f / sqrtf(wave_sum(ss) * (1.f / D) + EPS);
;         GAS f32x4* o = (GAS f32x4*)(O + (size_t)m * D) + 2 * F.lane;
; #pragma unroll
;         for (int j = 0; j < 8; ++j) { const int col = 8 * (F.lane + 64 * j); const f32x4 g0 = *(const f32x4*)(gain + col), g1 = *(const f32x4*)(gain + col + 4);
;             o[128 * j] = (f32x4){bflo(v[j].x), bfhi(v[j].x), bflo(v[j].y), bfhi(v[j].y)} * rstd * g0; o[128 * j + 1] = (f32x4){bflo(v[j].z), bfhi(v[j].z), bflo(v[j].w), bfhi(v[j].w)} * rstd * g1; }
	v_pk_fma_f32 v[126:127], v[46:47], v[46:47], v[128:129]
	v_pk_add_f32 v[118:119], v[122:123], v[122:123] op_sel:[0,1] op_sel_hi:[1,0]
	v_pk_add_f32 v[90:91], v[90:91], v[92:93]
	v_pk_mul_f32 v[132:133], v[42:43], v[42:43]
	v_pk_mul_f32 v[134:135], v[6:7], v[6:7]
	v_mul_f32_e32 v2, v15, v15
	v_mul_f32_e32 v4, v35, v35
	v_pk_fma_f32 v[128:129], v[36:37], v[36:37], v[130:131]
	v_pk_add_f32 v[112:113], v[126:127], v[118:119]
	v_pk_add_f32 v[90:91], v[90:91], v[98:99]
	v_mul_f32_e32 v54, v0, v0
	v_mul_f32_e32 v141, v1, v1
	v_pk_fma_f32 v[130:131], v[38:39], v[38:39], v[132:133]
	v_pk_fma_f32 v[132:133], v[8:9], v[8:9], v[134:135]
	v_pk_fma_f32 v[134:135], v[14:15], v[14:15], v[2:3] op_sel_hi:[1,1,0]
	v_pk_fma_f32 v[136:137], v[34:35], v[34:35], v[4:5] op_sel_hi:[1,1,0]
	v_pk_add_f32 v[120:121], v[128:129], v[128:129] op_sel:[0,1] op_sel_hi:[1,0]
	v_pk_add_f32 v[112:113], v[126:127], v[112:113] op_sel:[1,0] op_sel_hi:[0,1]
	v_pk_add_f32 v[90:91], v[90:91], v[90:91] op_sel:[0,1] op_sel_hi:[1,0]
	v_and_b32_e32 v13, 0xffff0000, v87
	v_and_b32_e32 v12, 0xffff0000, v86
	v_mov_b32_e32 v87, v5
	v_mov_b32_e32 v135, v54
	v_mov_b32_e32 v137, v141
	v_pk_add_f32 v[114:115], v[130:131], v[120:121]
	v_mov_b32_e32 v86, v112
	v_mov_b32_e32 v4, v90
	v_mul_f32_e32 v142, v3, v3
	v_pk_mul_f32 v[138:139], v[12:13], v[12:13]
	v_pk_add_f32 v[118:119], v[134:135], v[136:137]
	v_pk_add_f32 v[114:115], v[130:131], v[114:115] op_sel:[1,0] op_sel_hi:[0,1]
	v_pk_add_f32 v[90:91], v[90:91], v[112:113]
	v_pk_mul_f32 v[86:87], v[4:5], v[86:87]
	v_pk_fma_f32 v[122:123], v[10:11], v[10:11], v[138:139]
	v_pk_add_f32 v[116:117], v[132:133], v[118:119]
	v_mov_b32_e32 v115, v142
	v_mov_b32_e32 v91, v87
	v_pk_add_f32 v[110:111], v[122:123], v[116:117]
	v_pk_add_f32 v[86:87], v[90:91], v[114:115]
	s_nop 0
	v_pk_add_f32 v[86:87], v[86:87], v[110:111]
	s_nop 0
	v_add_f32_e32 v2, v86, v87
	ds_bpermute_b32 v4, v70, v2
	s_waitcnt lgkmcnt(0)
	v_add_f32_e32 v2, v2, v4
	ds_bpermute_b32 v4, v71, v2
	s_waitcnt lgkmcnt(0)
	v_add_f32_e32 v2, v2, v4
	ds_bpermute_b32 v4, v72, v2
	s_waitcnt lgkmcnt(0)
	v_add_f32_e32 v2, v2, v4
	ds_bpermute_b32 v4, v73, v2
	s_waitcnt lgkmcnt(0)
	v_add_f32_e32 v2, v2, v4
	ds_bpermute_b32 v4, v74, v2
	s_waitcnt lgkmcnt(0)
	v_add_f32_e32 v2, v2, v4
	ds_bpermute_b32 v4, v75, v2
	s_waitcnt lgkmcnt(0)
	v_add_f32_e32 v2, v2, v4
	v_fmamk_f32 v2, v2, 0x39800000, v76
	v_mul_f32_e32 v4, 0x4f800000, v2
	v_cmp_gt_f32_e32 vcc, s5, v2
	s_nop 1
	v_cndmask_b32_e32 v2, v2, v4, vcc
	v_sqrt_f32_e32 v4, v2
	s_nop 0
	v_add_u32_e32 v54, -1, v4
	v_add_u32_e32 v58, 1, v4
	v_fma_f32 v86, -v54, v4, v2
	v_fma_f32 v87, -v58, v4, v2
	v_cmp_ge_f32_e64 s[0:1], 0, v86
	s_nop 1
	v_cndmask_b32_e64 v4, v4, v54, s[0:1]
	v_cmp_lt_f32_e64 s[0:1], 0, v87
	s_nop 1
	v_cndmask_b32_e64 v4, v4, v58, s[0:1]
	v_mul_f32_e32 v54, 0x37800000, v4
	v_cndmask_b32_e32 v4, v4, v54, vcc
	v_cmp_class_f32_e32 vcc, v2, v77
	s_nop 1
	v_cndmask_b32_e32 v2, v4, v2, vcc
	v_div_scale_f32 v4, s[0:1], v2, v2, 1.0
	v_rcp_f32_e32 v58, v4
	v_div_scale_f32 v54, vcc, 1.0, v2, 1.0
	v_fma_f32 v86, -v4, v58, 1.0
	v_fmac_f32_e32 v58, v86, v58
	v_mul_f32_e32 v86, v54, v58
	v_fma_f32 v87, -v4, v86, v54
	v_fmac_f32_e32 v86, v87, v58
	v_fma_f32 v4, -v4, v86, v54
	v_div_fmas_f32 v4, v4, v58, v86
	v_div_fixup_f32 v4, v4, v2, 1.0
	v_pk_mul_f32 v[86:87], v[4:5], v[88:89] op_sel_hi:[0,1]
	v_pk_mul_f32 v[88:89], v[4:5], v[94:95] op_sel_hi:[0,1]
	v_pk_mul_f32 v[90:91], v[4:5], v[96:97] op_sel_hi:[0,1]
	v_pk_mul_f32 v[92:93], v[4:5], v[100:101] op_sel_hi:[0,1]
	v_pk_mul_f32 v[84:85], v[84:85], v[88:89]
	v_pk_mul_f32 v[82:83], v[82:83], v[86:87]
	v_pk_mul_f32 v[80:81], v[80:81], v[92:93]
	v_pk_mul_f32 v[78:79], v[78:79], v[90:91]
	global_store_dwordx4 v[30:31], v[82:85], off
	global_store_dwordx4 v[30:31], v[78:81], off offset:16
	s_nop 0
	v_mov_b32_e32 v86, v103
	v_mov_b32_e32 v87, v105
	v_mov_b32_e32 v103, v104
	v_mov_b32_e32 v88, v107
	v_mov_b32_e32 v89, v109
	v_mov_b32_e32 v107, v108
	v_pk_mul_f32 v[86:87], v[4:5], v[86:87] op_sel_hi:[0,1]
	v_pk_mul_f32 v[90:91], v[4:5], v[102:103] op_sel_hi:[0,1]
	v_pk_mul_f32 v[88:89], v[4:5], v[88:89] op_sel_hi:[0,1]
	v_pk_mul_f32 v[92:93], v[4:5], v[106:107] op_sel_hi:[0,1]
	v_pk_mul_f32 v[68:69], v[4:5], v[68:69] op_sel_hi:[0,1]
	v_pk_mul_f32 v[66:67], v[4:5], v[66:67] op_sel_hi:[0,1]
	v_mov_b32_e32 v54, v59
	v_pk_mul_f32 v[58:59], v[4:5], v[52:53] op_sel_hi:[0,1]
	v_pk_mul_f32 v[14:15], v[4:5], v[14:15] op_sel_hi:[0,1]
	v_mov_b32_e32 v2, v5
	v_mov_b32_e32 v78, v144
	v_mov_b32_e32 v79, v145
	v_mov_b32_e32 v80, v146
	v_mov_b32_e32 v81, v147
	v_pk_mul_f32 v[78:79], v[78:79], v[90:91]
	v_pk_mul_f32 v[80:81], v[80:81], v[86:87]
	v_mov_b32_e32 v82, v148
	v_mov_b32_e32 v83, v149
	v_mov_b32_e32 v84, v150
	v_mov_b32_e32 v85, v151
	v_pk_mul_f32 v[82:83], v[82:83], v[92:93]
	v_pk_mul_f32 v[84:85], v[84:85], v[88:89]
	global_store_dwordx4 v[30:31], v[78:81], off offset:2048
	global_store_dwordx4 v[30:31], v[82:85], off offset:2064
; #define GAS __attribute__((address_space(1)))
; __device__ __forceinline__ void final_norm_rows(Frame& F, const bf16* X, float* O, const float* gain) {
;     ...
;         GAS f32x4* o = (GAS f32x4*)(O + (size_t)m * D) + 2 * F.lane;
; #pragma unroll
;         for (int j = 0; j < 8; ++j) { const int col = 8 * (F.lane + 64 * j); const f32x4 g0 = *(const f32x4*)(gain + col), g1 = *(const f32x4*)(gain + col + 4);
;             o[128 * j] = (f32x4){bflo(v[j].x), bfhi(v[j].x), bflo(v[j].y), bfhi(v[j].y)} * rstd * g0; o[128 * j + 1] = (f32x4){bflo(v[j].z), bfhi(v[j].z), bflo(v[j].w), bfhi(v[j].w)} * rstd * g1; }
	s_nop 0
	v_add_co_u32_e32 v86, vcc, s3, v30
	v_mov_b32_e32 v90, v60
	s_nop 0
	v_addc_co_u32_e32 v87, vcc, 0, v31, vcc
	v_add_co_u32_e32 v88, vcc, s10, v30
	v_mov_b32_e32 v92, v64
	v_mov_b32_e32 v93, v56
	v_mov_b32_e32 v91, v62
	v_addc_co_u32_e32 v89, vcc, 0, v31, vcc
	v_pk_mul_f32 v[90:91], v[4:5], v[90:91] op_sel_hi:[0,1]
	v_pk_mul_f32 v[92:93], v[4:5], v[92:93] op_sel_hi:[0,1]
	v_mov_b32_e32 v56, v65
	v_mov_b32_e32 v62, v61
	v_pk_mul_f32 v[52:53], v[4:5], v[56:57] op_sel_hi:[0,1]
	v_pk_mul_f32 v[60:61], v[4:5], v[54:55] op_sel_hi:[0,1]
	v_pk_mul_f32 v[56:57], v[4:5], v[62:63] op_sel_hi:[0,1]
	v_mov_b32_e32 v62, v47
	v_mov_b32_e32 v63, v51
	v_mov_b32_e32 v47, v50
	v_pk_mul_f32 v[50:51], v[4:5], v[62:63] op_sel_hi:[0,1]
	v_mov_b32_e32 v78, v152
	v_mov_b32_e32 v79, v153
	v_mov_b32_e32 v80, v154
	v_mov_b32_e32 v81, v155
	v_pk_mul_f32 v[66:67], v[78:79], v[66:67]
	v_pk_mul_f32 v[68:69], v[80:81], v[68:69]
	v_mov_b32_e32 v82, v156
	v_mov_b32_e32 v83, v157
	v_mov_b32_e32 v84, v158
	v_mov_b32_e32 v85, v159
	v_pk_mul_f32 v[78:79], v[82:83], v[92:93]
	v_pk_mul_f32 v[80:81], v[84:85], v[90:91]
	global_store_dwordx4 v[88:89], v[66:69], off offset:-4096
	global_store_dwordx4 v[86:87], v[78:81], off offset:16
	s_nop 0
	v_mov_b32_e32 v66, v160
	v_mov_b32_e32 v67, v161
	v_mov_b32_e32 v68, v162
	v_mov_b32_e32 v69, v163
	v_pk_mul_f32 v[52:53], v[66:67], v[52:53]
	v_pk_mul_f32 v[54:55], v[68:69], v[58:59]
	v_mov_b32_e32 v78, v164
	v_mov_b32_e32 v79, v165
	v_mov_b32_e32 v80, v166
	v_mov_b32_e32 v81, v167
	v_pk_mul_f32 v[56:57], v[78:79], v[56:57]
	v_pk_mul_f32 v[58:59], v[80:81], v[60:61]
	global_store_dwordx4 v[86:87], v[52:55], off offset:2048
	global_store_dwordx4 v[86:87], v[56:59], off offset:2064
	s_nop 0
	v_mov_b32_e32 v60, v45
	v_mov_b32_e32 v61, v49
	v_mov_b32_e32 v45, v48
	v_pk_mul_f32 v[48:49], v[4:5], v[60:61] op_sel_hi:[0,1]
	v_pk_mul_f32 v[44:45], v[4:5], v[44:45] op_sel_hi:[0,1]
	v_pk_mul_f32 v[60:61], v[4:5], v[46:47] op_sel_hi:[0,1]
	v_mov_b32_e32 v52, v168
	v_mov_b32_e32 v53, v169
	v_mov_b32_e32 v54, v170
	v_mov_b32_e32 v55, v171
	v_pk_mul_f32 v[44:45], v[44:45], v[52:53]
	v_pk_mul_f32 v[46:47], v[48:49], v[54:55]
	v_mov_b32_e32 v56, v172
	v_mov_b32_e32 v57, v173
	v_mov_b32_e32 v58, v174
	v_mov_b32_e32 v59, v175
	v_pk_mul_f32 v[48:49], v[60:61], v[56:57]
	v_pk_mul_f32 v[50:51], v[50:51], v[58:59]
	global_store_dwordx4 v[88:89], v[44:47], off
	global_store_dwordx4 v[88:89], v[48:51], off offset:16
	s_nop 0
	v_mov_b32_e32 v52, v37
	v_mov_b32_e32 v53, v41
	v_mov_b32_e32 v37, v40
	v_mov_b32_e32 v54, v39
	v_mov_b32_e32 v55, v43
	v_mov_b32_e32 v39, v42
	v_pk_mul_f32 v[40:41], v[4:5], v[52:53] op_sel_hi:[0,1]
	v_pk_mul_f32 v[36:37], v[4:5], v[36:37] op_sel_hi:[0,1]
	v_pk_mul_f32 v[42:43], v[4:5], v[54:55] op_sel_hi:[0,1]
	v_pk_mul_f32 v[52:53], v[4:5], v[38:39] op_sel_hi:[0,1]
	v_mov_b32_e32 v44, v176
	v_mov_b32_e32 v45, v177
	v_mov_b32_e32 v46, v178
	v_mov_b32_e32 v47, v179
	v_pk_mul_f32 v[36:37], v[36:37], v[44:45]
	v_pk_mul_f32 v[38:39], v[40:41], v[46:47]
	v_mov_b32_e32 v48, v180
	v_mov_b32_e32 v49, v181
	v_mov_b32_e32 v50, v182
	v_mov_b32_e32 v51, v183
	v_pk_mul_f32 v[40:41], v[52:53], v[48:49]
	v_pk_mul_f32 v[42:43], v[42:43], v[50:51]
	global_store_dwordx4 v[88:89], v[36:39], off offset:2048
	global_store_dwordx4 v[88:89], v[40:43], off offset:2064
	s_nop 0
	v_add_co_u32_e32 v44, vcc, s11, v30
	v_mov_b32_e32 v46, v10
	v_mov_b32_e32 v48, v8
	v_mov_b32_e32 v49, v6
	v_mov_b32_e32 v47, v12
	v_pk_mul_f32 v[50:51], v[4:5], v[34:35] op_sel_hi:[0,1]
	v_addc_co_u32_e32 v45, vcc, 0, v31, vcc
	v_pk_mul_f32 v[46:47], v[4:5], v[46:47] op_sel_hi:[0,1]
	v_pk_mul_f32 v[48:49], v[4:5], v[48:49] op_sel_hi:[0,1]
	v_mov_b32_e32 v6, v9
	v_mov_b32_e32 v12, v11
	v_pk_mul_f32 v[8:9], v[4:5], v[0:1] op_sel_hi:[0,1]
	v_pk_mul_f32 v[0:1], v[4:5], v[6:7] op_sel_hi:[0,1]
	v_pk_mul_f32 v[6:7], v[4:5], v[2:3] op_sel_hi:[0,1]
	v_pk_mul_f32 v[4:5], v[4:5], v[12:13] op_sel_hi:[0,1]
	v_lshl_add_u64 v[30:31], v[30:31], 0, s[6:7]
	v_mov_b32_e32 v36, v184
	v_mov_b32_e32 v37, v185
	v_mov_b32_e32 v38, v186
	v_mov_b32_e32 v39, v187
	v_pk_mul_f32 v[34:35], v[14:15], v[36:37]
	v_pk_mul_f32 v[36:37], v[50:51], v[38:39]
	v_mov_b32_e32 v40, v188
	v_mov_b32_e32 v41, v189
	v_mov_b32_e32 v42, v190
	v_mov_b32_e32 v43, v191
	v_pk_mul_f32 v[38:39], v[48:49], v[40:41]
	v_pk_mul_f32 v[40:41], v[46:47], v[42:43]
	global_store_dwordx4 v[44:45], v[34:37], off
	global_store_dwordx4 v[44:45], v[38:41], off offset:16
	s_nop 0
	v_mov_b32_e32 v34, v192
	v_mov_b32_e32 v35, v193
	v_mov_b32_e32 v36, v194
	v_mov_b32_e32 v37, v195
	v_pk_mul_f32 v[0:1], v[0:1], v[34:35]
	v_pk_mul_f32 v[2:3], v[8:9], v[36:37]
	v_mov_b32_e32 v38, v196
	v_mov_b32_e32 v39, v197
	v_mov_b32_e32 v40, v198
	v_mov_b32_e32 v41, v199
	v_pk_mul_f32 v[4:5], v[4:5], v[38:39]
	v_pk_mul_f32 v[6:7], v[6:7], v[40:41]
	global_store_dwordx4 v[44:45], v[0:3], off offset:2048
	global_store_dwordx4 v[44:45], v[4:7], off offset:2064
	s_cbranch_scc1 .LBB0_1141
